# attention item output stores write-through (sc0 sc1)
# speedup vs baseline: 1.0040x; 1.0040x over previous
.LBB0_1065:
	v_mov_b32_e32 v0, v33
	s_getreg_b32 s2, hwreg(HW_REG_HW_ID, 0, 6)
	s_lshl_b32 s2, s2, 2
	s_and_b32 s2, s2, 0xfc
	s_add_i32 s2, s2, 0
	s_add_i32 s2, s2, 0x21100
	v_mov_b32_e32 v1, s2
	ds_read_b32 v1, v1
	v_mbcnt_lo_u32_b32 v0, -1, v0
	v_mbcnt_hi_u32_b32 v0, -1, v0
	s_mov_b64 s[2:3], 0
	v_lshlrev_b32_e32 v36, 16, v203
	s_waitcnt lgkmcnt(0)
	v_lshl_or_b32 v2, v1, 6, v0
	s_add_u32 s2, s76, s2
	s_addc_u32 s3, s77, s3
	s_add_i32 s96, s96, s87
	v_and_or_b32 v0, v2, 31, s96
	v_or_b32_e32 v32, s97, v0
	v_lshlrev_b64 v[0:1], 12, v[32:33]
	v_lshl_add_u64 v[0:1], s[2:3], 0, v[0:1]
	v_lshrrev_b32_e32 v2, 2, v2
	v_lshl_add_u64 v[0:1], s[84:85], 1, v[0:1]
	v_and_b32_e32 v32, 8, v2
	v_lshl_add_u64 v[2:3], v[0:1], 0, v[32:33]
	s_mov_b64 s[2:3], 0x25e51000
	v_lshl_add_u64 v[0:1], v[2:3], 0, s[2:3]
	s_mov_b32 s2, 0x25e51000
	v_add_co_u32_e32 v4, vcc, s2, v2
	v_and_b32_e32 v37, 0xffff0000, v203
	s_nop 0
	v_addc_co_u32_e32 v5, vcc, 0, v3, vcc
	v_mov_b32_e32 v34, v212
	v_mov_b32_e32 v35, v213
	v_mov_b32_e32 v30, v214
	v_mov_b32_e32 v31, v215
	v_mov_b32_e32 v28, v216
	v_mov_b32_e32 v29, v217
	v_mov_b32_e32 v26, v218
	v_mov_b32_e32 v27, v219
	v_mov_b32_e32 v24, v220
	v_mov_b32_e32 v25, v221
	v_mov_b32_e32 v22, v222
	v_mov_b32_e32 v23, v223
	v_mov_b32_e32 v20, v224
	v_mov_b32_e32 v21, v225
	v_mov_b32_e32 v18, v226
	v_mov_b32_e32 v19, v227
	v_mov_b32_e32 v16, v236
	v_mov_b32_e32 v17, v237
	v_mov_b32_e32 v14, v238
	v_mov_b32_e32 v15, v239
	v_mov_b32_e32 v12, v240
	v_mov_b32_e32 v13, v241
	v_mov_b32_e32 v10, v242
	v_mov_b32_e32 v11, v243
	v_mov_b32_e32 v8, v244
	v_mov_b32_e32 v9, v245
	v_mov_b32_e32 v6, v246
	v_mov_b32_e32 v7, v247
	v_mov_b32_e32 v4, v248
	v_mov_b32_e32 v5, v249
	s_nop 0
	v_mov_b32_e32 v0, v250
	v_mov_b32_e32 v1, v251
	s_mov_b32 s2, 0x29e51000
	v_add_co_u32_e32 v2, vcc, s2, v2
	s_waitcnt vmcnt(0)
	v_lshlrev_b32_e32 v38, 16, v34
	v_mul_f32_e32 v32, 0xbfb8aa3b, v38
	v_exp_f32_e32 v32, v32
	v_and_b32_e32 v39, 0xffff0000, v34
	v_addc_co_u32_e32 v3, vcc, 0, v3, vcc
	v_mbcnt_lo_u32_b32 v252, -1, 0
	v_mbcnt_hi_u32_b32 v252, -1, v252
	v_and_b32_e32 v252, 32, v252
	v_lshrrev_b32_e32 v252, 2, v252
	v_mov_b32_e32 v253, 0
	v_lshl_add_u64 v[228:229], v[2:3], 0, v[252:253]
	v_add_f32_e32 v32, 1.0, v32
	v_rcp_f32_e32 v40, v32
	v_mul_f32_e32 v32, 0xbfb8aa3b, v39
	v_exp_f32_e32 v32, v32
	s_nop 0
	v_add_f32_e32 v32, 1.0, v32
	v_rcp_f32_e32 v41, v32
	s_nop 0
	v_pk_mul_f32 v[38:39], v[40:41], v[38:39]
	s_nop 0
	v_pk_mul_f32 v[36:37], v[38:39], v[36:37]
	v_lshlrev_b32_e32 v38, 16, v35
	v_mul_f32_e32 v32, 0xbfb8aa3b, v38
	v_exp_f32_e32 v32, v32
	v_and_b32_e32 v39, 0xffff0000, v35
	v_cvt_pk_bf16_f32 v34, v36, v37
	v_lshlrev_b32_e32 v36, 16, v202
	v_add_f32_e32 v32, 1.0, v32
	v_rcp_f32_e32 v40, v32
	v_mul_f32_e32 v32, 0xbfb8aa3b, v39
	v_exp_f32_e32 v32, v32
	v_and_b32_e32 v37, 0xffff0000, v202
	v_add_f32_e32 v32, 1.0, v32
	v_rcp_f32_e32 v41, v32
	s_nop 0
	v_pk_mul_f32 v[38:39], v[40:41], v[38:39]
	s_nop 0
	v_pk_mul_f32 v[36:37], v[38:39], v[36:37]
	s_nop 0
	v_cvt_pk_bf16_f32 v35, v36, v37
	v_lshlrev_b32_e32 v36, 16, v30
	v_and_b32_e32 v37, 0xffff0000, v30
	v_mul_f32_e32 v30, 0xbfb8aa3b, v36
	v_exp_f32_e32 v30, v30
	v_mov_b32_e32 v212, v34
	v_mov_b32_e32 v213, v35
	v_lshlrev_b32_e32 v34, 16, v201
	v_and_b32_e32 v35, 0xffff0000, v201
	v_add_f32_e32 v30, 1.0, v30
	v_rcp_f32_e32 v38, v30
	v_mul_f32_e32 v30, 0xbfb8aa3b, v37
	v_exp_f32_e32 v30, v30
	s_nop 0
	v_add_f32_e32 v30, 1.0, v30
	v_rcp_f32_e32 v39, v30
	s_nop 0
	v_pk_mul_f32 v[36:37], v[38:39], v[36:37]
	s_nop 0
	v_pk_mul_f32 v[34:35], v[36:37], v[34:35]
	v_lshlrev_b32_e32 v36, 16, v31
	v_and_b32_e32 v37, 0xffff0000, v31
	v_mul_f32_e32 v31, 0xbfb8aa3b, v36
	v_exp_f32_e32 v31, v31
	v_cvt_pk_bf16_f32 v30, v34, v35
	v_lshlrev_b32_e32 v34, 16, v200
	v_and_b32_e32 v35, 0xffff0000, v200
	v_add_f32_e32 v31, 1.0, v31
	v_rcp_f32_e32 v38, v31
	v_mul_f32_e32 v31, 0xbfb8aa3b, v37
	v_exp_f32_e32 v31, v31
	s_nop 0
	v_add_f32_e32 v31, 1.0, v31
	v_rcp_f32_e32 v39, v31
	s_nop 0
	v_pk_mul_f32 v[36:37], v[38:39], v[36:37]
	s_nop 0
	v_pk_mul_f32 v[34:35], v[36:37], v[34:35]
	s_nop 0
	v_cvt_pk_bf16_f32 v31, v34, v35
	v_lshlrev_b32_e32 v34, 16, v28
	v_and_b32_e32 v35, 0xffff0000, v28
	v_mul_f32_e32 v28, 0xbfb8aa3b, v34
	v_exp_f32_e32 v28, v28
	v_mov_b32_e32 v214, v30
	v_mov_b32_e32 v215, v31
	s_nop 1
	v_permlane32_swap_b32_e32 v212, v214
	v_permlane32_swap_b32_e32 v213, v215
	global_store_dwordx4 v[228:229], v[212:215], off sc0 sc1
	v_lshlrev_b32_e32 v30, 16, v199
	v_and_b32_e32 v31, 0xffff0000, v199
	v_add_f32_e32 v28, 1.0, v28
	v_rcp_f32_e32 v36, v28
	v_mul_f32_e32 v28, 0xbfb8aa3b, v35
	v_exp_f32_e32 v28, v28
	s_nop 0
	v_add_f32_e32 v28, 1.0, v28
	v_rcp_f32_e32 v37, v28
	s_nop 0
	v_pk_mul_f32 v[34:35], v[36:37], v[34:35]
	s_nop 0
	v_pk_mul_f32 v[30:31], v[34:35], v[30:31]
	v_lshlrev_b32_e32 v34, 16, v29
	v_and_b32_e32 v35, 0xffff0000, v29
	v_mul_f32_e32 v29, 0xbfb8aa3b, v34
	v_exp_f32_e32 v29, v29
	v_cvt_pk_bf16_f32 v28, v30, v31
	v_lshlrev_b32_e32 v30, 16, v198
	v_and_b32_e32 v31, 0xffff0000, v198
	v_add_f32_e32 v29, 1.0, v29
	v_rcp_f32_e32 v36, v29
	v_mul_f32_e32 v29, 0xbfb8aa3b, v35
	v_exp_f32_e32 v29, v29
	s_nop 0
	v_add_f32_e32 v29, 1.0, v29
	v_rcp_f32_e32 v37, v29
	s_nop 0
	v_pk_mul_f32 v[34:35], v[36:37], v[34:35]
	s_nop 0
	v_pk_mul_f32 v[30:31], v[34:35], v[30:31]
	s_nop 0
	v_cvt_pk_bf16_f32 v29, v30, v31
	v_lshlrev_b32_e32 v30, 16, v26
	v_and_b32_e32 v31, 0xffff0000, v26
	v_mul_f32_e32 v26, 0xbfb8aa3b, v30
	v_exp_f32_e32 v26, v26
	v_mov_b32_e32 v216, v28
	v_mov_b32_e32 v217, v29
	v_lshlrev_b32_e32 v28, 16, v197
	v_and_b32_e32 v29, 0xffff0000, v197
	v_add_f32_e32 v26, 1.0, v26
	v_rcp_f32_e32 v34, v26
	v_mul_f32_e32 v26, 0xbfb8aa3b, v31
	v_exp_f32_e32 v26, v26
	s_nop 0
	v_add_f32_e32 v26, 1.0, v26
	v_rcp_f32_e32 v35, v26
	s_nop 0
	v_pk_mul_f32 v[30:31], v[34:35], v[30:31]
	s_nop 0
	v_pk_mul_f32 v[28:29], v[30:31], v[28:29]
	v_lshlrev_b32_e32 v30, 16, v27
	v_and_b32_e32 v31, 0xffff0000, v27
	v_mul_f32_e32 v27, 0xbfb8aa3b, v30
	v_exp_f32_e32 v27, v27
	v_cvt_pk_bf16_f32 v26, v28, v29
	v_lshlrev_b32_e32 v28, 16, v196
	v_and_b32_e32 v29, 0xffff0000, v196
	v_add_f32_e32 v27, 1.0, v27
	v_rcp_f32_e32 v34, v27
	v_mul_f32_e32 v27, 0xbfb8aa3b, v31
	v_exp_f32_e32 v27, v27
	s_nop 0
	v_add_f32_e32 v27, 1.0, v27
	v_rcp_f32_e32 v35, v27
	s_nop 0
	v_pk_mul_f32 v[30:31], v[34:35], v[30:31]
	s_nop 0
	v_pk_mul_f32 v[28:29], v[30:31], v[28:29]
	s_nop 0
	v_cvt_pk_bf16_f32 v27, v28, v29
	v_lshlrev_b32_e32 v28, 16, v24
	v_and_b32_e32 v29, 0xffff0000, v24
	v_mul_f32_e32 v24, 0xbfb8aa3b, v28
	v_exp_f32_e32 v24, v24
	v_mov_b32_e32 v218, v26
	v_mov_b32_e32 v219, v27
	s_nop 1
	v_permlane32_swap_b32_e32 v216, v218
	v_permlane32_swap_b32_e32 v217, v219
	global_store_dwordx4 v[228:229], v[216:219], off offset:32 sc0 sc1
	v_lshlrev_b32_e32 v26, 16, v195
	v_and_b32_e32 v27, 0xffff0000, v195
	v_add_f32_e32 v24, 1.0, v24
	v_rcp_f32_e32 v30, v24
	v_mul_f32_e32 v24, 0xbfb8aa3b, v29
	v_exp_f32_e32 v24, v24
	s_nop 0
	v_add_f32_e32 v24, 1.0, v24
	v_rcp_f32_e32 v31, v24
	s_nop 0
	v_pk_mul_f32 v[28:29], v[30:31], v[28:29]
	s_nop 0
	v_pk_mul_f32 v[26:27], v[28:29], v[26:27]
	v_lshlrev_b32_e32 v28, 16, v25
	v_and_b32_e32 v29, 0xffff0000, v25
	v_mul_f32_e32 v25, 0xbfb8aa3b, v28
	v_exp_f32_e32 v25, v25
	v_cvt_pk_bf16_f32 v24, v26, v27
	v_lshlrev_b32_e32 v26, 16, v194
	v_and_b32_e32 v27, 0xffff0000, v194
	v_add_f32_e32 v25, 1.0, v25
	v_rcp_f32_e32 v30, v25
	v_mul_f32_e32 v25, 0xbfb8aa3b, v29
	v_exp_f32_e32 v25, v25
	s_nop 0
	v_add_f32_e32 v25, 1.0, v25
	v_rcp_f32_e32 v31, v25
	s_nop 0
	v_pk_mul_f32 v[28:29], v[30:31], v[28:29]
	s_nop 0
	v_pk_mul_f32 v[26:27], v[28:29], v[26:27]
	s_nop 0
	v_cvt_pk_bf16_f32 v25, v26, v27
	v_lshlrev_b32_e32 v26, 16, v22
	v_and_b32_e32 v27, 0xffff0000, v22
	v_mul_f32_e32 v22, 0xbfb8aa3b, v26
	v_exp_f32_e32 v22, v22
	v_mov_b32_e32 v220, v24
	v_mov_b32_e32 v221, v25
	v_lshlrev_b32_e32 v24, 16, v193
	v_and_b32_e32 v25, 0xffff0000, v193
	v_add_f32_e32 v22, 1.0, v22
	v_rcp_f32_e32 v28, v22
	v_mul_f32_e32 v22, 0xbfb8aa3b, v27
	v_exp_f32_e32 v22, v22
	s_nop 0
	v_add_f32_e32 v22, 1.0, v22
	v_rcp_f32_e32 v29, v22
	s_nop 0
	v_pk_mul_f32 v[26:27], v[28:29], v[26:27]
	s_nop 0
	v_pk_mul_f32 v[24:25], v[26:27], v[24:25]
	v_lshlrev_b32_e32 v26, 16, v23
	v_and_b32_e32 v27, 0xffff0000, v23
	v_mul_f32_e32 v23, 0xbfb8aa3b, v26
	v_exp_f32_e32 v23, v23
	v_cvt_pk_bf16_f32 v22, v24, v25
	v_lshlrev_b32_e32 v24, 16, v192
	v_and_b32_e32 v25, 0xffff0000, v192
	v_add_f32_e32 v23, 1.0, v23
	v_rcp_f32_e32 v28, v23
	v_mul_f32_e32 v23, 0xbfb8aa3b, v27
	v_exp_f32_e32 v23, v23
	s_nop 0
	v_add_f32_e32 v23, 1.0, v23
	v_rcp_f32_e32 v29, v23
	s_nop 0
	v_pk_mul_f32 v[26:27], v[28:29], v[26:27]
	s_nop 0
	v_pk_mul_f32 v[24:25], v[26:27], v[24:25]
	s_nop 0
	v_cvt_pk_bf16_f32 v23, v24, v25
	v_lshlrev_b32_e32 v24, 16, v20
	v_and_b32_e32 v25, 0xffff0000, v20
	v_mul_f32_e32 v20, 0xbfb8aa3b, v24
	v_exp_f32_e32 v20, v20
	v_mov_b32_e32 v222, v22
	v_mov_b32_e32 v223, v23
	s_nop 1
	v_permlane32_swap_b32_e32 v220, v222
	v_permlane32_swap_b32_e32 v221, v223
	global_store_dwordx4 v[228:229], v[220:223], off offset:64 sc0 sc1
	v_lshlrev_b32_e32 v22, 16, v191
	v_and_b32_e32 v23, 0xffff0000, v191
	v_add_f32_e32 v20, 1.0, v20
	v_rcp_f32_e32 v26, v20
	v_mul_f32_e32 v20, 0xbfb8aa3b, v25
	v_exp_f32_e32 v20, v20
	s_nop 0
	v_add_f32_e32 v20, 1.0, v20
	v_rcp_f32_e32 v27, v20
	s_nop 0
	v_pk_mul_f32 v[24:25], v[26:27], v[24:25]
	s_nop 0
	v_pk_mul_f32 v[22:23], v[24:25], v[22:23]
	v_lshlrev_b32_e32 v24, 16, v21
	v_and_b32_e32 v25, 0xffff0000, v21
	v_mul_f32_e32 v21, 0xbfb8aa3b, v24
	v_exp_f32_e32 v21, v21
	v_cvt_pk_bf16_f32 v20, v22, v23
	v_lshlrev_b32_e32 v22, 16, v190
	v_and_b32_e32 v23, 0xffff0000, v190
	v_add_f32_e32 v21, 1.0, v21
	v_rcp_f32_e32 v26, v21
	v_mul_f32_e32 v21, 0xbfb8aa3b, v25
	v_exp_f32_e32 v21, v21
	s_nop 0
	v_add_f32_e32 v21, 1.0, v21
	v_rcp_f32_e32 v27, v21
	s_nop 0
	v_pk_mul_f32 v[24:25], v[26:27], v[24:25]
	s_nop 0
	v_pk_mul_f32 v[22:23], v[24:25], v[22:23]
	s_nop 0
	v_cvt_pk_bf16_f32 v21, v22, v23
	v_lshlrev_b32_e32 v22, 16, v18
	v_and_b32_e32 v23, 0xffff0000, v18
	v_mul_f32_e32 v18, 0xbfb8aa3b, v22
	v_exp_f32_e32 v18, v18
	v_mov_b32_e32 v224, v20
	v_mov_b32_e32 v225, v21
	v_lshlrev_b32_e32 v20, 16, v189
	v_and_b32_e32 v21, 0xffff0000, v189
	v_add_f32_e32 v18, 1.0, v18
	v_rcp_f32_e32 v24, v18
	v_mul_f32_e32 v18, 0xbfb8aa3b, v23
	v_exp_f32_e32 v18, v18
	s_nop 0
	v_add_f32_e32 v18, 1.0, v18
	v_rcp_f32_e32 v25, v18
	s_nop 0
	v_pk_mul_f32 v[22:23], v[24:25], v[22:23]
	s_nop 0
	v_pk_mul_f32 v[20:21], v[22:23], v[20:21]
	v_lshlrev_b32_e32 v22, 16, v19
	v_and_b32_e32 v23, 0xffff0000, v19
	v_mul_f32_e32 v19, 0xbfb8aa3b, v22
	v_exp_f32_e32 v19, v19
	v_cvt_pk_bf16_f32 v18, v20, v21
	v_lshlrev_b32_e32 v20, 16, v188
	v_and_b32_e32 v21, 0xffff0000, v188
	v_add_f32_e32 v19, 1.0, v19
	v_rcp_f32_e32 v24, v19
	v_mul_f32_e32 v19, 0xbfb8aa3b, v23
	v_exp_f32_e32 v19, v19
	s_nop 0
	v_add_f32_e32 v19, 1.0, v19
	v_rcp_f32_e32 v25, v19
	s_nop 0
	v_pk_mul_f32 v[22:23], v[24:25], v[22:23]
	s_nop 0
	v_pk_mul_f32 v[20:21], v[22:23], v[20:21]
	s_nop 0
	v_cvt_pk_bf16_f32 v19, v20, v21
	v_lshlrev_b32_e32 v20, 16, v16
	v_and_b32_e32 v21, 0xffff0000, v16
	v_mul_f32_e32 v16, 0xbfb8aa3b, v20
	v_exp_f32_e32 v16, v16
	v_mov_b32_e32 v226, v18
	v_mov_b32_e32 v227, v19
	s_nop 1
	v_permlane32_swap_b32_e32 v224, v226
	v_permlane32_swap_b32_e32 v225, v227
	global_store_dwordx4 v[228:229], v[224:227], off offset:96 sc0 sc1
	v_lshlrev_b32_e32 v18, 16, v187
	v_and_b32_e32 v19, 0xffff0000, v187
	v_add_f32_e32 v16, 1.0, v16
	v_rcp_f32_e32 v22, v16
	v_mul_f32_e32 v16, 0xbfb8aa3b, v21
	v_exp_f32_e32 v16, v16
	s_nop 0
	v_add_f32_e32 v16, 1.0, v16
	v_rcp_f32_e32 v23, v16
	s_nop 0
	v_pk_mul_f32 v[20:21], v[22:23], v[20:21]
	s_nop 0
	v_pk_mul_f32 v[18:19], v[20:21], v[18:19]
	v_lshlrev_b32_e32 v20, 16, v17
	v_and_b32_e32 v21, 0xffff0000, v17
	v_mul_f32_e32 v17, 0xbfb8aa3b, v20
	v_exp_f32_e32 v17, v17
	v_cvt_pk_bf16_f32 v16, v18, v19
	v_lshlrev_b32_e32 v18, 16, v186
	v_and_b32_e32 v19, 0xffff0000, v186
	v_add_f32_e32 v17, 1.0, v17
	v_rcp_f32_e32 v22, v17
	v_mul_f32_e32 v17, 0xbfb8aa3b, v21
	v_exp_f32_e32 v17, v17
	s_nop 0
	v_add_f32_e32 v17, 1.0, v17
	v_rcp_f32_e32 v23, v17
	s_nop 0
	v_pk_mul_f32 v[20:21], v[22:23], v[20:21]
	s_nop 0
	v_pk_mul_f32 v[18:19], v[20:21], v[18:19]
	s_nop 0
	v_cvt_pk_bf16_f32 v17, v18, v19
	v_lshlrev_b32_e32 v18, 16, v14
	v_and_b32_e32 v19, 0xffff0000, v14
	v_mul_f32_e32 v14, 0xbfb8aa3b, v18
	v_exp_f32_e32 v14, v14
	v_mov_b32_e32 v236, v16
	v_mov_b32_e32 v237, v17
	v_lshlrev_b32_e32 v16, 16, v185
	v_and_b32_e32 v17, 0xffff0000, v185
	v_add_f32_e32 v14, 1.0, v14
	v_rcp_f32_e32 v20, v14
	v_mul_f32_e32 v14, 0xbfb8aa3b, v19
	v_exp_f32_e32 v14, v14
	s_nop 0
	v_add_f32_e32 v14, 1.0, v14
	v_rcp_f32_e32 v21, v14
	s_nop 0
	v_pk_mul_f32 v[18:19], v[20:21], v[18:19]
	s_nop 0
	v_pk_mul_f32 v[16:17], v[18:19], v[16:17]
	v_lshlrev_b32_e32 v18, 16, v15
	v_and_b32_e32 v19, 0xffff0000, v15
	v_mul_f32_e32 v15, 0xbfb8aa3b, v18
	v_exp_f32_e32 v15, v15
	v_cvt_pk_bf16_f32 v14, v16, v17
	v_lshlrev_b32_e32 v16, 16, v184
	v_and_b32_e32 v17, 0xffff0000, v184
	v_add_f32_e32 v15, 1.0, v15
	v_rcp_f32_e32 v20, v15
	v_mul_f32_e32 v15, 0xbfb8aa3b, v19
	v_exp_f32_e32 v15, v15
	s_nop 0
	v_add_f32_e32 v15, 1.0, v15
	v_rcp_f32_e32 v21, v15
	s_nop 0
	v_pk_mul_f32 v[18:19], v[20:21], v[18:19]
	s_nop 0
	v_pk_mul_f32 v[16:17], v[18:19], v[16:17]
	s_nop 0
	v_cvt_pk_bf16_f32 v15, v16, v17
	v_lshlrev_b32_e32 v16, 16, v12
	v_and_b32_e32 v17, 0xffff0000, v12
	v_mul_f32_e32 v12, 0xbfb8aa3b, v16
	v_exp_f32_e32 v12, v12
	v_mov_b32_e32 v238, v14
	v_mov_b32_e32 v239, v15
	s_nop 1
	v_permlane32_swap_b32_e32 v236, v238
	v_permlane32_swap_b32_e32 v237, v239
	global_store_dwordx4 v[228:229], v[236:239], off offset:128 sc0 sc1
	v_lshlrev_b32_e32 v14, 16, v183
	v_and_b32_e32 v15, 0xffff0000, v183
	v_add_f32_e32 v12, 1.0, v12
	v_rcp_f32_e32 v18, v12
	v_mul_f32_e32 v12, 0xbfb8aa3b, v17
	v_exp_f32_e32 v12, v12
	s_nop 0
	v_add_f32_e32 v12, 1.0, v12
	v_rcp_f32_e32 v19, v12
	s_nop 0
	v_pk_mul_f32 v[16:17], v[18:19], v[16:17]
	s_nop 0
	v_pk_mul_f32 v[14:15], v[16:17], v[14:15]
	v_lshlrev_b32_e32 v16, 16, v13
	v_and_b32_e32 v17, 0xffff0000, v13
	v_mul_f32_e32 v13, 0xbfb8aa3b, v16
	v_exp_f32_e32 v13, v13
	v_cvt_pk_bf16_f32 v12, v14, v15
	v_lshlrev_b32_e32 v14, 16, v182
	v_and_b32_e32 v15, 0xffff0000, v182
	v_add_f32_e32 v13, 1.0, v13
	v_rcp_f32_e32 v18, v13
	v_mul_f32_e32 v13, 0xbfb8aa3b, v17
	v_exp_f32_e32 v13, v13
	s_nop 0
	v_add_f32_e32 v13, 1.0, v13
	v_rcp_f32_e32 v19, v13
	s_nop 0
	v_pk_mul_f32 v[16:17], v[18:19], v[16:17]
	s_nop 0
	v_pk_mul_f32 v[14:15], v[16:17], v[14:15]
	s_nop 0
	v_cvt_pk_bf16_f32 v13, v14, v15
	v_lshlrev_b32_e32 v14, 16, v10
	v_and_b32_e32 v15, 0xffff0000, v10
	v_mul_f32_e32 v10, 0xbfb8aa3b, v14
	v_exp_f32_e32 v10, v10
	v_mov_b32_e32 v240, v12
	v_mov_b32_e32 v241, v13
	v_lshlrev_b32_e32 v12, 16, v181
	v_and_b32_e32 v13, 0xffff0000, v181
	v_add_f32_e32 v10, 1.0, v10
	v_rcp_f32_e32 v16, v10
	v_mul_f32_e32 v10, 0xbfb8aa3b, v15
	v_exp_f32_e32 v10, v10
	s_nop 0
	v_add_f32_e32 v10, 1.0, v10
	v_rcp_f32_e32 v17, v10
	s_nop 0
	v_pk_mul_f32 v[14:15], v[16:17], v[14:15]
	s_nop 0
	v_pk_mul_f32 v[12:13], v[14:15], v[12:13]
	v_lshlrev_b32_e32 v14, 16, v11
	v_and_b32_e32 v15, 0xffff0000, v11
	v_mul_f32_e32 v11, 0xbfb8aa3b, v14
	v_exp_f32_e32 v11, v11
	v_cvt_pk_bf16_f32 v10, v12, v13
	v_lshlrev_b32_e32 v12, 16, v180
	v_and_b32_e32 v13, 0xffff0000, v180
	v_add_f32_e32 v11, 1.0, v11
	v_rcp_f32_e32 v16, v11
	v_mul_f32_e32 v11, 0xbfb8aa3b, v15
	v_exp_f32_e32 v11, v11
	s_nop 0
	v_add_f32_e32 v11, 1.0, v11
	v_rcp_f32_e32 v17, v11
	s_nop 0
	v_pk_mul_f32 v[14:15], v[16:17], v[14:15]
	s_nop 0
	v_pk_mul_f32 v[12:13], v[14:15], v[12:13]
	s_nop 0
	v_cvt_pk_bf16_f32 v11, v12, v13
	v_lshlrev_b32_e32 v12, 16, v8
	v_and_b32_e32 v13, 0xffff0000, v8
	v_mul_f32_e32 v8, 0xbfb8aa3b, v12
	v_exp_f32_e32 v8, v8
	v_mov_b32_e32 v242, v10
	v_mov_b32_e32 v243, v11
	s_nop 1
	v_permlane32_swap_b32_e32 v240, v242
	v_permlane32_swap_b32_e32 v241, v243
	global_store_dwordx4 v[228:229], v[240:243], off offset:160 sc0 sc1
	v_lshlrev_b32_e32 v10, 16, v177
	v_and_b32_e32 v11, 0xffff0000, v177
	v_add_f32_e32 v8, 1.0, v8
	v_rcp_f32_e32 v14, v8
	v_mul_f32_e32 v8, 0xbfb8aa3b, v13
	v_exp_f32_e32 v8, v8
	s_nop 0
	v_add_f32_e32 v8, 1.0, v8
	v_rcp_f32_e32 v15, v8
	s_nop 0
	v_pk_mul_f32 v[12:13], v[14:15], v[12:13]
	s_nop 0
	v_pk_mul_f32 v[10:11], v[12:13], v[10:11]
	v_lshlrev_b32_e32 v12, 16, v9
	v_and_b32_e32 v13, 0xffff0000, v9
	v_mul_f32_e32 v9, 0xbfb8aa3b, v12
	v_exp_f32_e32 v9, v9
	v_cvt_pk_bf16_f32 v8, v10, v11
	v_lshlrev_b32_e32 v10, 16, v176
	v_and_b32_e32 v11, 0xffff0000, v176
	v_add_f32_e32 v9, 1.0, v9
	v_rcp_f32_e32 v14, v9
	v_mul_f32_e32 v9, 0xbfb8aa3b, v13
	v_exp_f32_e32 v9, v9
	s_nop 0
	v_add_f32_e32 v9, 1.0, v9
	v_rcp_f32_e32 v15, v9
	s_nop 0
	v_pk_mul_f32 v[12:13], v[14:15], v[12:13]
	s_nop 0
	v_pk_mul_f32 v[10:11], v[12:13], v[10:11]
	s_nop 0
	v_cvt_pk_bf16_f32 v9, v10, v11
	v_lshlrev_b32_e32 v10, 16, v6
	v_and_b32_e32 v11, 0xffff0000, v6
	v_mul_f32_e32 v6, 0xbfb8aa3b, v10
	v_exp_f32_e32 v6, v6
	v_mov_b32_e32 v244, v8
	v_mov_b32_e32 v245, v9
	v_lshlrev_b32_e32 v8, 16, v175
	v_and_b32_e32 v9, 0xffff0000, v175
	v_add_f32_e32 v6, 1.0, v6
	v_rcp_f32_e32 v12, v6
	v_mul_f32_e32 v6, 0xbfb8aa3b, v11
	v_exp_f32_e32 v6, v6
	s_nop 0
	v_add_f32_e32 v6, 1.0, v6
	v_rcp_f32_e32 v13, v6
	s_nop 0
	v_pk_mul_f32 v[10:11], v[12:13], v[10:11]
	s_nop 0
	v_pk_mul_f32 v[8:9], v[10:11], v[8:9]
	v_lshlrev_b32_e32 v10, 16, v7
	v_and_b32_e32 v11, 0xffff0000, v7
	v_mul_f32_e32 v7, 0xbfb8aa3b, v10
	v_exp_f32_e32 v7, v7
	v_cvt_pk_bf16_f32 v6, v8, v9
	v_lshlrev_b32_e32 v8, 16, v174
	v_and_b32_e32 v9, 0xffff0000, v174
	v_add_f32_e32 v7, 1.0, v7
	v_rcp_f32_e32 v12, v7
	v_mul_f32_e32 v7, 0xbfb8aa3b, v11
	v_exp_f32_e32 v7, v7
	s_nop 0
	v_add_f32_e32 v7, 1.0, v7
	v_rcp_f32_e32 v13, v7
	s_nop 0
	v_pk_mul_f32 v[10:11], v[12:13], v[10:11]
	s_nop 0
	v_pk_mul_f32 v[8:9], v[10:11], v[8:9]
	s_nop 0
	v_cvt_pk_bf16_f32 v7, v8, v9
	v_lshlrev_b32_e32 v8, 16, v4
	v_and_b32_e32 v9, 0xffff0000, v4
	v_mul_f32_e32 v4, 0xbfb8aa3b, v8
	v_exp_f32_e32 v4, v4
	v_mov_b32_e32 v246, v6
	v_mov_b32_e32 v247, v7
	s_nop 1
	v_permlane32_swap_b32_e32 v244, v246
	v_permlane32_swap_b32_e32 v245, v247
	global_store_dwordx4 v[228:229], v[244:247], off offset:192 sc0 sc1
	v_lshlrev_b32_e32 v6, 16, v173
	v_and_b32_e32 v7, 0xffff0000, v173
	v_add_f32_e32 v4, 1.0, v4
	v_rcp_f32_e32 v10, v4
	v_mul_f32_e32 v4, 0xbfb8aa3b, v9
	v_exp_f32_e32 v4, v4
	s_nop 0
	v_add_f32_e32 v4, 1.0, v4
	v_rcp_f32_e32 v11, v4
	s_nop 0
	v_pk_mul_f32 v[8:9], v[10:11], v[8:9]
	s_nop 0
	v_pk_mul_f32 v[6:7], v[8:9], v[6:7]
	v_lshlrev_b32_e32 v8, 16, v5
	v_and_b32_e32 v9, 0xffff0000, v5
	v_mul_f32_e32 v5, 0xbfb8aa3b, v8
	v_exp_f32_e32 v5, v5
	v_cvt_pk_bf16_f32 v4, v6, v7
	v_lshlrev_b32_e32 v6, 16, v172
	v_and_b32_e32 v7, 0xffff0000, v172
	v_add_f32_e32 v5, 1.0, v5
	v_rcp_f32_e32 v10, v5
	v_mul_f32_e32 v5, 0xbfb8aa3b, v9
	v_exp_f32_e32 v5, v5
	s_nop 0
	v_add_f32_e32 v5, 1.0, v5
	v_rcp_f32_e32 v11, v5
	s_nop 0
	v_pk_mul_f32 v[8:9], v[10:11], v[8:9]
	s_nop 0
	v_pk_mul_f32 v[6:7], v[8:9], v[6:7]
	s_nop 0
	v_cvt_pk_bf16_f32 v5, v6, v7
	v_lshlrev_b32_e32 v6, 16, v0
	v_and_b32_e32 v7, 0xffff0000, v0
	v_mul_f32_e32 v0, 0xbfb8aa3b, v6
	v_exp_f32_e32 v0, v0
	v_mov_b32_e32 v248, v4
	v_mov_b32_e32 v249, v5
	v_lshlrev_b32_e32 v4, 16, v171
	v_and_b32_e32 v5, 0xffff0000, v171
	v_add_f32_e32 v0, 1.0, v0
	v_rcp_f32_e32 v8, v0
	v_mul_f32_e32 v0, 0xbfb8aa3b, v7
	v_exp_f32_e32 v0, v0
	s_nop 0
	v_add_f32_e32 v0, 1.0, v0
	v_rcp_f32_e32 v9, v0
	s_nop 0
	v_pk_mul_f32 v[6:7], v[8:9], v[6:7]
	s_nop 0
	v_pk_mul_f32 v[4:5], v[6:7], v[4:5]
	v_lshlrev_b32_e32 v6, 16, v1
	v_and_b32_e32 v7, 0xffff0000, v1
	v_mul_f32_e32 v1, 0xbfb8aa3b, v6
	v_exp_f32_e32 v1, v1
	v_cvt_pk_bf16_f32 v0, v4, v5
	v_lshlrev_b32_e32 v4, 16, v170
	v_and_b32_e32 v5, 0xffff0000, v170
	v_add_f32_e32 v1, 1.0, v1
	v_rcp_f32_e32 v8, v1
	v_mul_f32_e32 v1, 0xbfb8aa3b, v7
	v_exp_f32_e32 v1, v1
	s_nop 0
	v_add_f32_e32 v1, 1.0, v1
	v_rcp_f32_e32 v9, v1
	s_nop 0
	v_pk_mul_f32 v[6:7], v[8:9], v[6:7]
	s_nop 0
	v_pk_mul_f32 v[4:5], v[6:7], v[4:5]
	s_nop 0
	v_cvt_pk_bf16_f32 v1, v4, v5
	v_mov_b32_e32 v250, v0
	v_mov_b32_e32 v251, v1
	s_nop 1
	v_permlane32_swap_b32_e32 v248, v250
	v_permlane32_swap_b32_e32 v249, v251
	global_store_dwordx4 v[228:229], v[248:251], off offset:224 sc0 sc1
